# combo8 + up-GEMM LDS-DMA loads use SGPR base + 32-bit VGPR offset (drops 64-bit per-lane address adds from the load segments)
# speedup vs baseline: 1.0053x; 1.0053x over previous
; #define PG8_STAGE(bufoff, gbase, voff) do { _Pragma("unroll") for (int _i = 0; _i < 2; ++_i) \
;         __builtin_amdgcn_global_load_lds((const unsigned*)((const char*)(gbase) + (voff)[_i]), (PG8_LAS unsigned*)(lds + (bufoff) + ldsw + _i * 8192), 16, 0, 0); } while (0)
; #define PG8_LDA(dst, b, h) do { _Pragma("unroll") for (int m = 0; m < 4; ++m) _Pragma("unroll") for (int k = 0; k < 2; ++k) dst[m][k] = *(const PG8_LAS bf16x8*)(lds + PG8_SA(b, h) + aoff + m * 2048 + k * 1024); } while (0)
; #define PG8_LDB(dst, b, h) do { _Pragma("unroll") for (int n = 0; n < 2; ++n) _Pragma("unroll") for (int k = 0; k < 2; ++k) dst[n][k] = *(const PG8_LAS bf16x8*)(lds + PG8_SB(b, h) + boff + n * 2048 + k * 1024); } while (0)
; #define PG8_MMA(ai, bj, At, Bt) do { __builtin_amdgcn_s_setprio(1); _Pragma("unroll") for (int m = 0; m < 4; ++m) _Pragma("unroll") for (int n = 0; n < 2; ++n) _Pragma("unroll") for (int k = 0; k < 2; ++k) \
;         acc[ai][bj][m][n] = __builtin_amdgcn_mfma_f32_16x16x32_bf16(Bt[n][k], At[m][k], acc[ai][bj][m][n], 0, 0, 0); __builtin_amdgcn_s_setprio(0); } while (0)
; #define PG8_WAIT_V(n) asm volatile("s_waitcnt vmcnt(" #n ")" ::: "memory")
; #define PG8_WAIT_L(n) asm volatile("s_waitcnt lgkmcnt(" #n ")" ::: "memory")
; #define PG8_BAR __builtin_amdgcn_s_barrier()
; #define PG8_SCHED __builtin_amdgcn_sched_barrier(0)
; template <class Epi, class Sched, bool ALIGN_EPI = false, bool SP2 = false>
; __device__ __forceinline__ void gemm_phase(PG8_LAS unsigned char* lds, const Gemm g, const Sched& S, const Epi& E, const int tid) {
;     ...
;             PG8_LDB(B0, 0, 0); PG8_LDB(B1, 0, 1); PG8_SCHED; PG8_LDA(At, 0, 0); PG8_STAGE(PG8_SA(1, 1), a1 + hstep, voffA);
;             PG8_WAIT_V(8); PG8_WAIT_L(0); PG8_BAR; PG8_MMA(0, 0, At, B0); PG8_MMA(0, 1, At, B1); PG8_BAR; PG8_SCHED;
;             PG8_LDA(At, 0, 1); PG8_STAGE(PG8_SB(0, 0), b2, voffB); PG8_STAGE(PG8_SB(0, 1), b2 + hstep, voffB); PG8_STAGE(PG8_SA(0, 0), a2, voffA);
;             PG8_WAIT_V(8); PG8_WAIT_L(0); PG8_BAR; PG8_MMA(1, 0, At, B0); PG8_MMA(1, 1, At, B1); PG8_BAR; PG8_SCHED;
.Lup_peel:
	s_add_u32 s28, s24, 0xfff80080
	s_addc_u32 s29, s25, -1
	s_and_b64 s[26:27], s[26:27], exec
	s_cselect_b32 s29, s17, s29
	s_cselect_b32 s28, s75, s28
	s_cselect_b32 s27, s15, s50
	s_cselect_b32 s26, s85, s23
	s_add_i32 s42, 0, 0x10000
	v_add_u32_e32 v134, s42, v161
	s_add_i32 s43, 0, 0x14000
	ds_read_b128 v[140:143], v134
	ds_read_b128 v[144:147], v134 offset:1024
	ds_read_b128 v[166:169], v134 offset:2048
	ds_read_b128 v[170:173], v134 offset:3072
	v_add_u32_e32 v134, s43, v161
	ds_read_b128 v[174:177], v134
	ds_read_b128 v[186:189], v134 offset:1024
	ds_read_b128 v[190:193], v134 offset:2048
	ds_read_b128 v[194:197], v134 offset:3072
	s_nop 0
	s_add_i32 m0, s37, 0xc000
	ds_read_b128 v[198:201], v165
	ds_read_b128 v[202:205], v165 offset:1024
	ds_read_b128 v[206:209], v165 offset:2048
	ds_read_b128 v[210:213], v165 offset:3072
	ds_read_b128 v[214:217], v165 offset:4096
	ds_read_b128 v[218:221], v165 offset:5120
	ds_read_b128 v[222:225], v165 offset:6144
	ds_read_b128 v[226:229], v165 offset:7168
	global_load_lds_dwordx4 v156, s[24:25]
	s_nop 0
	s_add_i32 m0, s37, 0xe000
	s_nop 0
	global_load_lds_dwordx4 v158, s[24:25]
	s_waitcnt vmcnt(8)
	s_waitcnt lgkmcnt(0)
	s_setprio 1
	s_barrier
	v_mfma_f32_16x16x32_bf16 v[134:137], v[140:143], v[198:201], 0
	v_mfma_f32_16x16x32_bf16 v[124:127], v[166:169], v[198:201], 0
	v_mfma_f32_16x16x32_bf16 v[112:115], v[140:143], v[206:209], 0
	v_mfma_f32_16x16x32_bf16 v[108:111], v[166:169], v[206:209], 0
	v_mfma_f32_16x16x32_bf16 v[96:99], v[140:143], v[214:217], 0
	v_mfma_f32_16x16x32_bf16 v[92:95], v[166:169], v[214:217], 0
	v_mfma_f32_16x16x32_bf16 v[80:83], v[140:143], v[222:225], 0
	v_mfma_f32_16x16x32_bf16 v[76:79], v[166:169], v[222:225], 0
	v_mfma_f32_16x16x32_bf16 v[134:137], v[144:147], v[202:205], v[134:137]
	v_mfma_f32_16x16x32_bf16 v[124:127], v[170:173], v[202:205], v[124:127]
	v_mfma_f32_16x16x32_bf16 v[112:115], v[144:147], v[210:213], v[112:115]
	v_mfma_f32_16x16x32_bf16 v[108:111], v[170:173], v[210:213], v[108:111]
	v_mfma_f32_16x16x32_bf16 v[96:99], v[144:147], v[218:221], v[96:99]
	v_mfma_f32_16x16x32_bf16 v[92:95], v[170:173], v[218:221], v[92:95]
	v_mfma_f32_16x16x32_bf16 v[80:83], v[144:147], v[226:229], v[80:83]
	v_mfma_f32_16x16x32_bf16 v[76:79], v[170:173], v[226:229], v[76:79]
	s_setprio 0
	s_setprio 1
	v_mfma_f32_16x16x32_bf16 v[120:123], v[174:177], v[198:201], 0
	v_mfma_f32_16x16x32_bf16 v[116:119], v[190:193], v[198:201], 0
	v_mfma_f32_16x16x32_bf16 v[104:107], v[174:177], v[206:209], 0
	v_mfma_f32_16x16x32_bf16 v[100:103], v[190:193], v[206:209], 0
	v_mfma_f32_16x16x32_bf16 v[88:91], v[174:177], v[214:217], 0
	v_mfma_f32_16x16x32_bf16 v[84:87], v[190:193], v[214:217], 0
	v_mfma_f32_16x16x32_bf16 v[72:75], v[174:177], v[222:225], 0
	v_mfma_f32_16x16x32_bf16 v[68:71], v[190:193], v[222:225], 0
	v_mfma_f32_16x16x32_bf16 v[120:123], v[186:189], v[202:205], v[120:123]
	v_mfma_f32_16x16x32_bf16 v[116:119], v[194:197], v[202:205], v[116:119]
	v_mfma_f32_16x16x32_bf16 v[104:107], v[186:189], v[210:213], v[104:107]
	v_mfma_f32_16x16x32_bf16 v[100:103], v[194:197], v[210:213], v[100:103]
	v_mfma_f32_16x16x32_bf16 v[88:91], v[186:189], v[218:221], v[88:91]
	v_mfma_f32_16x16x32_bf16 v[84:87], v[194:197], v[218:221], v[84:87]
	v_mfma_f32_16x16x32_bf16 v[72:75], v[186:189], v[226:229], v[72:75]
	v_mfma_f32_16x16x32_bf16 v[68:71], v[194:197], v[226:229], v[68:71]
	s_setprio 0
	s_barrier
	s_add_i32 s42, s42, s31
	v_lshl_add_u64 v[178:179], s[26:27], 0, v[2:3]
	s_mov_b32 m0, s42
	ds_read_b128 v[198:201], v165 offset:16384
	ds_read_b128 v[202:205], v165 offset:17408
	ds_read_b128 v[206:209], v165 offset:18432
	ds_read_b128 v[210:213], v165 offset:19456
	ds_read_b128 v[214:217], v165 offset:20480
	ds_read_b128 v[218:221], v165 offset:21504
	ds_read_b128 v[222:225], v165 offset:22528
	ds_read_b128 v[226:229], v165 offset:23552
	global_load_lds_dwordx4 v[178:179], off
	s_add_i32 m0, s42, 0x2000
	s_add_u32 s94, s26, 0x80000
	v_lshl_add_u64 v[180:181], s[26:27], 0, v[0:1]
	s_addc_u32 s95, s27, 0
	s_add_i32 s42, s43, s31
	global_load_lds_dwordx4 v[180:181], off
	s_nop 0
	s_mov_b32 m0, s42
	v_lshl_add_u64 v[182:183], s[28:29], 0, v[150:151]
	global_load_lds_dwordx4 v2, s[94:95]
	v_lshl_add_u64 v[138:139], s[94:95], 0, v[0:1]
	s_add_i32 m0, s42, 0x2000
	v_lshl_add_u64 v[230:231], s[28:29], 0, v[148:149]
	global_load_lds_dwordx4 v[138:139], off
	s_mov_b32 m0, s37
	s_nop 0
	global_load_lds_dwordx4 v[182:183], off
	s_mov_b32 m0, s39
	s_nop 0
	global_load_lds_dwordx4 v[230:231], off
	s_waitcnt vmcnt(8)
	s_waitcnt lgkmcnt(0)
	s_setprio 1
	s_barrier
; #define PG8_STAGE(bufoff, gbase, voff) do { _Pragma("unroll") for (int _i = 0; _i < 2; ++_i) \
;         __builtin_amdgcn_global_load_lds((const unsigned*)((const char*)(gbase) + (voff)[_i]), (PG8_LAS unsigned*)(lds + (bufoff) + ldsw + _i * 8192), 16, 0, 0); } while (0)
; #define PG8_LDA(dst, b, h) do { _Pragma("unroll") for (int m = 0; m < 4; ++m) _Pragma("unroll") for (int k = 0; k < 2; ++k) dst[m][k] = *(const PG8_LAS bf16x8*)(lds + PG8_SA(b, h) + aoff + m * 2048 + k * 1024); } while (0)
; #define PG8_LDB(dst, b, h) do { _Pragma("unroll") for (int n = 0; n < 2; ++n) _Pragma("unroll") for (int k = 0; k < 2; ++k) dst[n][k] = *(const PG8_LAS bf16x8*)(lds + PG8_SB(b, h) + boff + n * 2048 + k * 1024); } while (0)
; #define PG8_MMA(ai, bj, At, Bt) do { __builtin_amdgcn_s_setprio(1); _Pragma("unroll") for (int m = 0; m < 4; ++m) _Pragma("unroll") for (int n = 0; n < 2; ++n) _Pragma("unroll") for (int k = 0; k < 2; ++k) \
;         acc[ai][bj][m][n] = __builtin_amdgcn_mfma_f32_16x16x32_bf16(Bt[n][k], At[m][k], acc[ai][bj][m][n], 0, 0, 0); __builtin_amdgcn_s_setprio(0); } while (0)
; #define PG8_WAIT_V(n) asm volatile("s_waitcnt vmcnt(" #n ")" ::: "memory")
; #define PG8_WAIT_L(n) asm volatile("s_waitcnt lgkmcnt(" #n ")" ::: "memory")
; #define PG8_BAR __builtin_amdgcn_s_barrier()
; #define PG8_SCHED __builtin_amdgcn_sched_barrier(0)
; template <class Epi, class Sched, bool ALIGN_EPI = false, bool SP2 = false>
; __device__ __forceinline__ void gemm_phase(PG8_LAS unsigned char* lds, const Gemm g, const Sched& S, const Epi& E, const int tid) {
;     ...
;             PG8_WAIT_V(8); PG8_WAIT_L(0); PG8_BAR; PG8_MMA(1, 0, At, B0); PG8_MMA(1, 1, At, B1); PG8_BAR; PG8_SCHED;
;             PG8_LDB(B0, 1, 0); PG8_LDB(B1, 1, 1); PG8_SCHED; PG8_LDA(At, 1, 0); PG8_STAGE(PG8_SA(0, 1), a2 + hstep, voffA);
;             PG8_WAIT_V(8); PG8_WAIT_L(0); PG8_BAR; PG8_MMA(0, 0, At, B0); PG8_MMA(0, 1, At, B1); PG8_BAR; PG8_SCHED;
	v_mfma_f32_16x16x32_bf16 v[64:67], v[140:143], v[198:201], 0
	v_mfma_f32_16x16x32_bf16 v[60:63], v[166:169], v[198:201], 0
	v_mfma_f32_16x16x32_bf16 v[48:51], v[140:143], v[206:209], 0
	v_mfma_f32_16x16x32_bf16 v[44:47], v[166:169], v[206:209], 0
	v_mfma_f32_16x16x32_bf16 v[32:35], v[140:143], v[214:217], 0
	v_mfma_f32_16x16x32_bf16 v[28:31], v[166:169], v[214:217], 0
	v_mfma_f32_16x16x32_bf16 v[16:19], v[140:143], v[222:225], 0
	v_mfma_f32_16x16x32_bf16 v[12:15], v[166:169], v[222:225], 0
	v_mfma_f32_16x16x32_bf16 v[64:67], v[144:147], v[202:205], v[64:67]
	v_mfma_f32_16x16x32_bf16 v[60:63], v[170:173], v[202:205], v[60:63]
	v_mfma_f32_16x16x32_bf16 v[48:51], v[144:147], v[210:213], v[48:51]
	v_mfma_f32_16x16x32_bf16 v[44:47], v[170:173], v[210:213], v[44:47]
	v_mfma_f32_16x16x32_bf16 v[32:35], v[144:147], v[218:221], v[32:35]
	v_mfma_f32_16x16x32_bf16 v[28:31], v[170:173], v[218:221], v[28:31]
	v_mfma_f32_16x16x32_bf16 v[16:19], v[144:147], v[226:229], v[16:19]
	v_mfma_f32_16x16x32_bf16 v[12:15], v[170:173], v[226:229], v[12:15]
	s_setprio 0
	s_setprio 1
	v_mfma_f32_16x16x32_bf16 v[56:59], v[174:177], v[198:201], 0
	v_mfma_f32_16x16x32_bf16 v[52:55], v[190:193], v[198:201], 0
	v_mfma_f32_16x16x32_bf16 v[40:43], v[174:177], v[206:209], 0
	v_mfma_f32_16x16x32_bf16 v[36:39], v[190:193], v[206:209], 0
	v_mfma_f32_16x16x32_bf16 v[24:27], v[174:177], v[214:217], 0
	v_mfma_f32_16x16x32_bf16 v[20:23], v[190:193], v[214:217], 0
	v_mfma_f32_16x16x32_bf16 v[8:11], v[174:177], v[222:225], 0
	v_mfma_f32_16x16x32_bf16 v[4:7], v[190:193], v[222:225], 0
	v_mfma_f32_16x16x32_bf16 v[56:59], v[186:189], v[202:205], v[56:59]
	v_mfma_f32_16x16x32_bf16 v[52:55], v[194:197], v[202:205], v[52:55]
	v_mfma_f32_16x16x32_bf16 v[40:43], v[186:189], v[210:213], v[40:43]
	v_mfma_f32_16x16x32_bf16 v[36:39], v[194:197], v[210:213], v[36:39]
	v_mfma_f32_16x16x32_bf16 v[24:27], v[186:189], v[218:221], v[24:27]
	v_mfma_f32_16x16x32_bf16 v[20:23], v[194:197], v[218:221], v[20:23]
	v_mfma_f32_16x16x32_bf16 v[8:11], v[186:189], v[226:229], v[8:11]
	v_mfma_f32_16x16x32_bf16 v[4:7], v[194:197], v[226:229], v[4:7]
	s_setprio 0
	s_barrier
	s_add_i32 s42, 0, 0x18000
	v_add_u32_e32 v138, s42, v161
	s_add_i32 s43, 0, 0x1c000
	ds_read_b128 v[140:143], v138
	ds_read_b128 v[144:147], v138 offset:1024
	ds_read_b128 v[166:169], v138 offset:2048
	ds_read_b128 v[170:173], v138 offset:3072
	v_add_u32_e32 v138, s43, v161
	ds_read_b128 v[174:177], v138
	ds_read_b128 v[186:189], v138 offset:1024
	ds_read_b128 v[190:193], v138 offset:2048
	ds_read_b128 v[194:197], v138 offset:3072
	s_add_u32 s28, s28, 0x80000
	s_addc_u32 s29, s29, 0
	s_mov_b32 m0, s44
	s_nop 0
	ds_read_b128 v[198:201], v165 offset:32768
	ds_read_b128 v[202:205], v165 offset:33792
	ds_read_b128 v[206:209], v165 offset:34816
	ds_read_b128 v[210:213], v165 offset:35840
	ds_read_b128 v[214:217], v165 offset:36864
	ds_read_b128 v[218:221], v165 offset:37888
	ds_read_b128 v[222:225], v165 offset:38912
	ds_read_b128 v[226:229], v165 offset:39936
	global_load_lds_dwordx4 v150, s[28:29]
	s_nop 0
	s_mov_b32 m0, s48
	s_nop 0
	global_load_lds_dwordx4 v148, s[28:29]
	s_waitcnt vmcnt(8)
	s_waitcnt lgkmcnt(0)
	s_setprio 1
	s_barrier
	v_mfma_f32_16x16x32_bf16 v[134:137], v[140:143], v[198:201], v[134:137]
	v_mfma_f32_16x16x32_bf16 v[124:127], v[166:169], v[198:201], v[124:127]
	v_mfma_f32_16x16x32_bf16 v[112:115], v[140:143], v[206:209], v[112:115]
	v_mfma_f32_16x16x32_bf16 v[108:111], v[166:169], v[206:209], v[108:111]
	v_mfma_f32_16x16x32_bf16 v[96:99], v[140:143], v[214:217], v[96:99]
	v_mfma_f32_16x16x32_bf16 v[92:95], v[166:169], v[214:217], v[92:95]
	v_mfma_f32_16x16x32_bf16 v[80:83], v[140:143], v[222:225], v[80:83]
	v_mfma_f32_16x16x32_bf16 v[76:79], v[166:169], v[222:225], v[76:79]
	v_mfma_f32_16x16x32_bf16 v[136:139], v[144:147], v[202:205], v[134:137]
	v_mfma_f32_16x16x32_bf16 v[124:127], v[170:173], v[202:205], v[124:127]
	v_mfma_f32_16x16x32_bf16 v[112:115], v[144:147], v[210:213], v[112:115]
	v_mfma_f32_16x16x32_bf16 v[108:111], v[170:173], v[210:213], v[108:111]
	v_mfma_f32_16x16x32_bf16 v[96:99], v[144:147], v[218:221], v[96:99]
	v_mfma_f32_16x16x32_bf16 v[92:95], v[170:173], v[218:221], v[92:95]
	v_mfma_f32_16x16x32_bf16 v[80:83], v[144:147], v[226:229], v[80:83]
	v_mfma_f32_16x16x32_bf16 v[76:79], v[170:173], v[226:229], v[76:79]
	s_setprio 0
	s_setprio 1
	v_mfma_f32_16x16x32_bf16 v[120:123], v[174:177], v[198:201], v[120:123]
	v_mfma_f32_16x16x32_bf16 v[116:119], v[190:193], v[198:201], v[116:119]
	v_mfma_f32_16x16x32_bf16 v[104:107], v[174:177], v[206:209], v[104:107]
	v_mfma_f32_16x16x32_bf16 v[100:103], v[190:193], v[206:209], v[100:103]
	v_mfma_f32_16x16x32_bf16 v[88:91], v[174:177], v[214:217], v[88:91]
	v_mfma_f32_16x16x32_bf16 v[84:87], v[190:193], v[214:217], v[84:87]
	v_mfma_f32_16x16x32_bf16 v[72:75], v[174:177], v[222:225], v[72:75]
	v_mfma_f32_16x16x32_bf16 v[68:71], v[190:193], v[222:225], v[68:71]
	v_mfma_f32_16x16x32_bf16 v[120:123], v[186:189], v[202:205], v[120:123]
	v_mfma_f32_16x16x32_bf16 v[116:119], v[194:197], v[202:205], v[116:119]
	v_mfma_f32_16x16x32_bf16 v[104:107], v[186:189], v[210:213], v[104:107]
	v_mfma_f32_16x16x32_bf16 v[100:103], v[194:197], v[210:213], v[100:103]
	v_mfma_f32_16x16x32_bf16 v[88:91], v[186:189], v[218:221], v[88:91]
	v_mfma_f32_16x16x32_bf16 v[84:87], v[194:197], v[218:221], v[84:87]
	v_mfma_f32_16x16x32_bf16 v[72:75], v[186:189], v[226:229], v[72:75]
	v_mfma_f32_16x16x32_bf16 v[68:71], v[194:197], v[226:229], v[68:71]
	s_setprio 0
	s_barrier
; #define PG8_STAGE(bufoff, gbase, voff) do { _Pragma("unroll") for (int _i = 0; _i < 2; ++_i) \
;         __builtin_amdgcn_global_load_lds((const unsigned*)((const char*)(gbase) + (voff)[_i]), (PG8_LAS unsigned*)(lds + (bufoff) + ldsw + _i * 8192), 16, 0, 0); } while (0)
; #define PG8_LDA(dst, b, h) do { _Pragma("unroll") for (int m = 0; m < 4; ++m) _Pragma("unroll") for (int k = 0; k < 2; ++k) dst[m][k] = *(const PG8_LAS bf16x8*)(lds + PG8_SA(b, h) + aoff + m * 2048 + k * 1024); } while (0)
; #define PG8_LDB(dst, b, h) do { _Pragma("unroll") for (int n = 0; n < 2; ++n) _Pragma("unroll") for (int k = 0; k < 2; ++k) dst[n][k] = *(const PG8_LAS bf16x8*)(lds + PG8_SB(b, h) + boff + n * 2048 + k * 1024); } while (0)
; #define PG8_MMA(ai, bj, At, Bt) do { __builtin_amdgcn_s_setprio(1); _Pragma("unroll") for (int m = 0; m < 4; ++m) _Pragma("unroll") for (int n = 0; n < 2; ++n) _Pragma("unroll") for (int k = 0; k < 2; ++k) \
;         acc[ai][bj][m][n] = __builtin_amdgcn_mfma_f32_16x16x32_bf16(Bt[n][k], At[m][k], acc[ai][bj][m][n], 0, 0, 0); __builtin_amdgcn_s_setprio(0); } while (0)
; #define PG8_BAR __builtin_amdgcn_s_barrier()
; template <class Epi, class Sched, bool ALIGN_EPI = false, bool SP2 = false>
; __device__ __forceinline__ void gemm_phase(PG8_LAS unsigned char* lds, const Gemm g, const Sched& S, const Epi& E, const int tid) {
;     ...
;             PG8_LDB(B0, 0, 0); PG8_LDB(B1, 0, 1); PG8_SCHED; PG8_LDA(At, 0, 0); PG8_STAGE(PG8_SA(1, 1), a1 + hstep, voffA);
;             PG8_WAIT_V(8); PG8_WAIT_L(0); PG8_BAR; PG8_MMA(0, 0, At, B0); PG8_MMA(0, 1, At, B1); PG8_BAR; PG8_SCHED;
;             PG8_LDA(At, 0, 1); PG8_STAGE(PG8_SB(0, 0), b2, voffB); PG8_STAGE(PG8_SB(0, 1), b2 + hstep, voffB); PG8_STAGE(PG8_SA(0, 0), a2, voffA);
;             PG8_WAIT_V(8); PG8_WAIT_L(0); PG8_BAR; PG8_MMA(1, 0, At, B0); PG8_MMA(1, 1, At, B1); PG8_BAR; PG8_SCHED;
;             PG8_LDB(B0, 1, 0); PG8_LDB(B1, 1, 1); PG8_SCHED; PG8_LDA(At, 1, 0); PG8_STAGE(PG8_SA(0, 1), a2 + hstep, voffA);
;             PG8_WAIT_V(8); PG8_WAIT_L(0); PG8_BAR; PG8_MMA(0, 0, At, B0); PG8_MMA(0, 1, At, B1); PG8_BAR; PG8_SCHED;
;             PG8_LDA(At, 1, 1); PG8_STAGE(PG8_SB(1, 0), b3, voffB); PG8_STAGE(PG8_SB(1, 1), b3 + hstep, voffB); PG8_STAGE(PG8_SA(1, 0), a3, voffA);
;             PG8_WAIT_V(8); PG8_WAIT_L(0); PG8_BAR; PG8_MMA(1, 0, At, B0); PG8_MMA(1, 1, At, B1); PG8_BAR; PG8_SCHED;
	s_add_i32 s28, s42, s31
	v_lshl_add_u64 v[134:135], v[178:179], 0, s[46:47]
	s_mov_b32 m0, s28
	ds_read_b128 v[198:201], v165 offset:49152
	ds_read_b128 v[202:205], v165 offset:50176
	ds_read_b128 v[206:209], v165 offset:51200
	ds_read_b128 v[210:213], v165 offset:52224
	ds_read_b128 v[214:217], v165 offset:53248
	ds_read_b128 v[218:221], v165 offset:54272
	ds_read_b128 v[222:225], v165 offset:55296
	ds_read_b128 v[226:229], v165 offset:56320
	global_load_lds_dwordx4 v[134:135], off
	s_add_i32 m0, s28, 0x2000
	s_add_u32 s26, s26, 0x80080
	v_lshl_add_u64 v[134:135], v[180:181], 0, s[46:47]
	s_addc_u32 s27, s27, 0
	s_add_i32 s28, s43, s31
	global_load_lds_dwordx4 v[134:135], off
	s_nop 0
	s_mov_b32 m0, s28
	s_nop 0
	global_load_lds_dwordx4 v2, s[26:27]
	v_lshl_add_u64 v[134:135], s[26:27], 0, v[0:1]
	s_add_i32 m0, s28, 0x2000
	s_nop 0
	global_load_lds_dwordx4 v[134:135], off
	v_lshl_add_u64 v[134:135], v[182:183], 0, s[46:47]
	s_mov_b32 m0, s52
	s_nop 0
	global_load_lds_dwordx4 v[134:135], off
	v_lshl_add_u64 v[134:135], v[230:231], 0, s[46:47]
	s_mov_b32 m0, s53
	s_nop 0
	global_load_lds_dwordx4 v[134:135], off
	s_waitcnt vmcnt(8)
	s_waitcnt lgkmcnt(0)
	s_setprio 1
	s_barrier
	v_mfma_f32_16x16x32_bf16 v[64:67], v[140:143], v[198:201], v[64:67]
	v_mfma_f32_16x16x32_bf16 v[60:63], v[166:169], v[198:201], v[60:63]
	v_mfma_f32_16x16x32_bf16 v[48:51], v[140:143], v[206:209], v[48:51]
	v_mfma_f32_16x16x32_bf16 v[44:47], v[166:169], v[206:209], v[44:47]
	v_mfma_f32_16x16x32_bf16 v[32:35], v[140:143], v[214:217], v[32:35]
	v_mfma_f32_16x16x32_bf16 v[28:31], v[166:169], v[214:217], v[28:31]
	v_mfma_f32_16x16x32_bf16 v[16:19], v[140:143], v[222:225], v[16:19]
	v_mfma_f32_16x16x32_bf16 v[12:15], v[166:169], v[222:225], v[12:15]
	v_mfma_f32_16x16x32_bf16 v[64:67], v[144:147], v[202:205], v[64:67]
	v_mfma_f32_16x16x32_bf16 v[60:63], v[170:173], v[202:205], v[60:63]
	v_mfma_f32_16x16x32_bf16 v[48:51], v[144:147], v[210:213], v[48:51]
	v_mfma_f32_16x16x32_bf16 v[44:47], v[170:173], v[210:213], v[44:47]
	v_mfma_f32_16x16x32_bf16 v[32:35], v[144:147], v[218:221], v[32:35]
	v_mfma_f32_16x16x32_bf16 v[28:31], v[170:173], v[218:221], v[28:31]
	v_mfma_f32_16x16x32_bf16 v[16:19], v[144:147], v[226:229], v[16:19]
	v_mfma_f32_16x16x32_bf16 v[12:15], v[170:173], v[226:229], v[12:15]
	s_setprio 0
	s_setprio 1
	v_mfma_f32_16x16x32_bf16 v[56:59], v[174:177], v[198:201], v[56:59]
	v_mfma_f32_16x16x32_bf16 v[52:55], v[190:193], v[198:201], v[52:55]
	v_mfma_f32_16x16x32_bf16 v[40:43], v[174:177], v[206:209], v[40:43]
	v_mfma_f32_16x16x32_bf16 v[36:39], v[190:193], v[206:209], v[36:39]
	v_mfma_f32_16x16x32_bf16 v[24:27], v[174:177], v[214:217], v[24:27]
	v_mfma_f32_16x16x32_bf16 v[20:23], v[190:193], v[214:217], v[20:23]
	v_mfma_f32_16x16x32_bf16 v[8:11], v[174:177], v[222:225], v[8:11]
	v_mfma_f32_16x16x32_bf16 v[4:7], v[190:193], v[222:225], v[4:7]
	v_mfma_f32_16x16x32_bf16 v[56:59], v[186:189], v[202:205], v[56:59]
	v_mfma_f32_16x16x32_bf16 v[52:55], v[194:197], v[202:205], v[52:55]
	v_mfma_f32_16x16x32_bf16 v[40:43], v[186:189], v[210:213], v[40:43]
	v_mfma_f32_16x16x32_bf16 v[36:39], v[194:197], v[210:213], v[36:39]
	v_mfma_f32_16x16x32_bf16 v[24:27], v[186:189], v[218:221], v[24:27]
	v_mfma_f32_16x16x32_bf16 v[20:23], v[194:197], v[218:221], v[20:23]
	v_mfma_f32_16x16x32_bf16 v[8:11], v[186:189], v[226:229], v[8:11]
	v_mfma_f32_16x16x32_bf16 v[4:7], v[194:197], v[226:229], v[4:7]
	s_setprio 0
	s_barrier
	s_add_i32 s51, s51, 2
	s_add_u32 s24, s24, 0x100
	s_addc_u32 s25, s25, 0
	s_add_u32 s23, s23, 0x100
	s_addc_u32 s50, s50, 0
	s_cmp_gt_u32 s51, 29
	s_cbranch_scc1 .LBB0_269
	s_branch .LBB0_267
.LBB0_266:
	s_add_u32 s28, s24, 0xfff80080
	s_addc_u32 s29, s25, -1
	s_and_b64 s[26:27], s[26:27], exec
	s_cselect_b32 s29, s17, s29
	s_cselect_b32 s28, s75, s28
	s_cselect_b32 s27, s15, s50
	s_cselect_b32 s26, s85, s23
	s_add_i32 s42, 0, 0x10000
	v_add_u32_e32 v134, s42, v161
	s_add_i32 s43, 0, 0x14000
	ds_read_b128 v[140:143], v134
	ds_read_b128 v[144:147], v134 offset:1024
	ds_read_b128 v[166:169], v134 offset:2048
	ds_read_b128 v[170:173], v134 offset:3072
	v_add_u32_e32 v134, s43, v161
	ds_read_b128 v[174:177], v134
	ds_read_b128 v[186:189], v134 offset:1024
	ds_read_b128 v[190:193], v134 offset:2048
	ds_read_b128 v[194:197], v134 offset:3072
	s_nop 0
	s_add_i32 m0, s37, 0xc000
	ds_read_b128 v[198:201], v165
	ds_read_b128 v[202:205], v165 offset:1024
	ds_read_b128 v[206:209], v165 offset:2048
	ds_read_b128 v[210:213], v165 offset:3072
	ds_read_b128 v[214:217], v165 offset:4096
	ds_read_b128 v[218:221], v165 offset:5120
	ds_read_b128 v[222:225], v165 offset:6144
	ds_read_b128 v[226:229], v165 offset:7168
	global_load_lds_dwordx4 v156, s[24:25]
	s_nop 0
	s_add_i32 m0, s37, 0xe000
	s_nop 0
	global_load_lds_dwordx4 v158, s[24:25]
	s_waitcnt vmcnt(8)
	s_waitcnt lgkmcnt(0)
	s_setprio 1
	s_barrier
; #define PG8_STAGE(bufoff, gbase, voff) do { _Pragma("unroll") for (int _i = 0; _i < 2; ++_i) \
;         __builtin_amdgcn_global_load_lds((const unsigned*)((const char*)(gbase) + (voff)[_i]), (PG8_LAS unsigned*)(lds + (bufoff) + ldsw + _i * 8192), 16, 0, 0); } while (0)
; #define PG8_LDA(dst, b, h) do { _Pragma("unroll") for (int m = 0; m < 4; ++m) _Pragma("unroll") for (int k = 0; k < 2; ++k) dst[m][k] = *(const PG8_LAS bf16x8*)(lds + PG8_SA(b, h) + aoff + m * 2048 + k * 1024); } while (0)
; #define PG8_LDB(dst, b, h) do { _Pragma("unroll") for (int n = 0; n < 2; ++n) _Pragma("unroll") for (int k = 0; k < 2; ++k) dst[n][k] = *(const PG8_LAS bf16x8*)(lds + PG8_SB(b, h) + boff + n * 2048 + k * 1024); } while (0)
; #define PG8_MMA(ai, bj, At, Bt) do { __builtin_amdgcn_s_setprio(1); _Pragma("unroll") for (int m = 0; m < 4; ++m) _Pragma("unroll") for (int n = 0; n < 2; ++n) _Pragma("unroll") for (int k = 0; k < 2; ++k) \
;         acc[ai][bj][m][n] = __builtin_amdgcn_mfma_f32_16x16x32_bf16(Bt[n][k], At[m][k], acc[ai][bj][m][n], 0, 0, 0); __builtin_amdgcn_s_setprio(0); } while (0)
; #define PG8_WAIT_V(n) asm volatile("s_waitcnt vmcnt(" #n ")" ::: "memory")
; #define PG8_WAIT_L(n) asm volatile("s_waitcnt lgkmcnt(" #n ")" ::: "memory")
; #define PG8_BAR __builtin_amdgcn_s_barrier()
; #define PG8_SCHED __builtin_amdgcn_sched_barrier(0)
; template <class Epi, class Sched, bool ALIGN_EPI = false, bool SP2 = false>
; __device__ __forceinline__ void gemm_phase(PG8_LAS unsigned char* lds, const Gemm g, const Sched& S, const Epi& E, const int tid) {
;     ...
;             PG8_LDB(B0, 0, 0); PG8_LDB(B1, 0, 1); PG8_SCHED; PG8_LDA(At, 0, 0); PG8_STAGE(PG8_SA(1, 1), a1 + hstep, voffA);
;             PG8_WAIT_V(8); PG8_WAIT_L(0); PG8_BAR; PG8_MMA(0, 0, At, B0); PG8_MMA(0, 1, At, B1); PG8_BAR; PG8_SCHED;
;             PG8_LDA(At, 0, 1); PG8_STAGE(PG8_SB(0, 0), b2, voffB); PG8_STAGE(PG8_SB(0, 1), b2 + hstep, voffB); PG8_STAGE(PG8_SA(0, 0), a2, voffA);
;             PG8_WAIT_V(8); PG8_WAIT_L(0); PG8_BAR; PG8_MMA(1, 0, At, B0); PG8_MMA(1, 1, At, B1); PG8_BAR; PG8_SCHED;
	v_mfma_f32_16x16x32_bf16 v[134:137], v[140:143], v[198:201], v[136:139]
	v_mfma_f32_16x16x32_bf16 v[124:127], v[166:169], v[198:201], v[124:127]
	v_mfma_f32_16x16x32_bf16 v[112:115], v[140:143], v[206:209], v[112:115]
	v_mfma_f32_16x16x32_bf16 v[108:111], v[166:169], v[206:209], v[108:111]
	v_mfma_f32_16x16x32_bf16 v[96:99], v[140:143], v[214:217], v[96:99]
	v_mfma_f32_16x16x32_bf16 v[92:95], v[166:169], v[214:217], v[92:95]
	v_mfma_f32_16x16x32_bf16 v[80:83], v[140:143], v[222:225], v[80:83]
	v_mfma_f32_16x16x32_bf16 v[76:79], v[166:169], v[222:225], v[76:79]
	v_mfma_f32_16x16x32_bf16 v[134:137], v[144:147], v[202:205], v[134:137]
	v_mfma_f32_16x16x32_bf16 v[124:127], v[170:173], v[202:205], v[124:127]
	v_mfma_f32_16x16x32_bf16 v[112:115], v[144:147], v[210:213], v[112:115]
	v_mfma_f32_16x16x32_bf16 v[108:111], v[170:173], v[210:213], v[108:111]
	v_mfma_f32_16x16x32_bf16 v[96:99], v[144:147], v[218:221], v[96:99]
	v_mfma_f32_16x16x32_bf16 v[92:95], v[170:173], v[218:221], v[92:95]
	v_mfma_f32_16x16x32_bf16 v[80:83], v[144:147], v[226:229], v[80:83]
	v_mfma_f32_16x16x32_bf16 v[76:79], v[170:173], v[226:229], v[76:79]
	s_setprio 0
	s_setprio 1
	v_mfma_f32_16x16x32_bf16 v[120:123], v[174:177], v[198:201], v[120:123]
	v_mfma_f32_16x16x32_bf16 v[116:119], v[190:193], v[198:201], v[116:119]
	v_mfma_f32_16x16x32_bf16 v[104:107], v[174:177], v[206:209], v[104:107]
	v_mfma_f32_16x16x32_bf16 v[100:103], v[190:193], v[206:209], v[100:103]
	v_mfma_f32_16x16x32_bf16 v[88:91], v[174:177], v[214:217], v[88:91]
	v_mfma_f32_16x16x32_bf16 v[84:87], v[190:193], v[214:217], v[84:87]
	v_mfma_f32_16x16x32_bf16 v[72:75], v[174:177], v[222:225], v[72:75]
	v_mfma_f32_16x16x32_bf16 v[68:71], v[190:193], v[222:225], v[68:71]
	v_mfma_f32_16x16x32_bf16 v[120:123], v[186:189], v[202:205], v[120:123]
	v_mfma_f32_16x16x32_bf16 v[116:119], v[194:197], v[202:205], v[116:119]
	v_mfma_f32_16x16x32_bf16 v[104:107], v[186:189], v[210:213], v[104:107]
	v_mfma_f32_16x16x32_bf16 v[100:103], v[194:197], v[210:213], v[100:103]
	v_mfma_f32_16x16x32_bf16 v[88:91], v[186:189], v[218:221], v[88:91]
	v_mfma_f32_16x16x32_bf16 v[84:87], v[194:197], v[218:221], v[84:87]
	v_mfma_f32_16x16x32_bf16 v[72:75], v[186:189], v[226:229], v[72:75]
	v_mfma_f32_16x16x32_bf16 v[68:71], v[194:197], v[226:229], v[68:71]
	s_setprio 0
	s_barrier
	s_add_i32 s42, s42, s31
	v_lshl_add_u64 v[178:179], s[26:27], 0, v[2:3]
	s_mov_b32 m0, s42
	ds_read_b128 v[198:201], v165 offset:16384
	ds_read_b128 v[202:205], v165 offset:17408
	ds_read_b128 v[206:209], v165 offset:18432
	ds_read_b128 v[210:213], v165 offset:19456
	ds_read_b128 v[214:217], v165 offset:20480
	ds_read_b128 v[218:221], v165 offset:21504
	ds_read_b128 v[222:225], v165 offset:22528
	ds_read_b128 v[226:229], v165 offset:23552
	global_load_lds_dwordx4 v[178:179], off
	s_add_i32 m0, s42, 0x2000
	s_add_u32 s94, s26, 0x80000
	v_lshl_add_u64 v[180:181], s[26:27], 0, v[0:1]
	s_addc_u32 s95, s27, 0
	s_add_i32 s42, s43, s31
	global_load_lds_dwordx4 v[180:181], off
	s_nop 0
	s_mov_b32 m0, s42
	v_lshl_add_u64 v[182:183], s[28:29], 0, v[150:151]
	global_load_lds_dwordx4 v2, s[94:95]
	v_lshl_add_u64 v[138:139], s[94:95], 0, v[0:1]
	s_add_i32 m0, s42, 0x2000
	v_lshl_add_u64 v[230:231], s[28:29], 0, v[148:149]
	global_load_lds_dwordx4 v[138:139], off
	s_mov_b32 m0, s37
	s_nop 0
	global_load_lds_dwordx4 v[182:183], off
	s_mov_b32 m0, s39
	s_nop 0
	global_load_lds_dwordx4 v[230:231], off
	s_waitcnt vmcnt(8)
	s_waitcnt lgkmcnt(0)
	s_setprio 1
	s_barrier
	v_mfma_f32_16x16x32_bf16 v[64:67], v[140:143], v[198:201], v[64:67]
	v_mfma_f32_16x16x32_bf16 v[60:63], v[166:169], v[198:201], v[60:63]
	v_mfma_f32_16x16x32_bf16 v[48:51], v[140:143], v[206:209], v[48:51]
	v_mfma_f32_16x16x32_bf16 v[44:47], v[166:169], v[206:209], v[44:47]
	v_mfma_f32_16x16x32_bf16 v[32:35], v[140:143], v[214:217], v[32:35]
	v_mfma_f32_16x16x32_bf16 v[28:31], v[166:169], v[214:217], v[28:31]
	v_mfma_f32_16x16x32_bf16 v[16:19], v[140:143], v[222:225], v[16:19]
	v_mfma_f32_16x16x32_bf16 v[12:15], v[166:169], v[222:225], v[12:15]
	v_mfma_f32_16x16x32_bf16 v[64:67], v[144:147], v[202:205], v[64:67]
	v_mfma_f32_16x16x32_bf16 v[60:63], v[170:173], v[202:205], v[60:63]
	v_mfma_f32_16x16x32_bf16 v[48:51], v[144:147], v[210:213], v[48:51]
	v_mfma_f32_16x16x32_bf16 v[44:47], v[170:173], v[210:213], v[44:47]
	v_mfma_f32_16x16x32_bf16 v[32:35], v[144:147], v[218:221], v[32:35]
	v_mfma_f32_16x16x32_bf16 v[28:31], v[170:173], v[218:221], v[28:31]
	v_mfma_f32_16x16x32_bf16 v[16:19], v[144:147], v[226:229], v[16:19]
	v_mfma_f32_16x16x32_bf16 v[12:15], v[170:173], v[226:229], v[12:15]
	s_setprio 0
	s_setprio 1
	v_mfma_f32_16x16x32_bf16 v[56:59], v[174:177], v[198:201], v[56:59]
	v_mfma_f32_16x16x32_bf16 v[52:55], v[190:193], v[198:201], v[52:55]
	v_mfma_f32_16x16x32_bf16 v[40:43], v[174:177], v[206:209], v[40:43]
	v_mfma_f32_16x16x32_bf16 v[36:39], v[190:193], v[206:209], v[36:39]
	v_mfma_f32_16x16x32_bf16 v[24:27], v[174:177], v[214:217], v[24:27]
	v_mfma_f32_16x16x32_bf16 v[20:23], v[190:193], v[214:217], v[20:23]
	v_mfma_f32_16x16x32_bf16 v[8:11], v[174:177], v[222:225], v[8:11]
	v_mfma_f32_16x16x32_bf16 v[4:7], v[190:193], v[222:225], v[4:7]
	v_mfma_f32_16x16x32_bf16 v[56:59], v[186:189], v[202:205], v[56:59]
	v_mfma_f32_16x16x32_bf16 v[52:55], v[194:197], v[202:205], v[52:55]
	v_mfma_f32_16x16x32_bf16 v[40:43], v[186:189], v[210:213], v[40:43]
	v_mfma_f32_16x16x32_bf16 v[36:39], v[194:197], v[210:213], v[36:39]
	v_mfma_f32_16x16x32_bf16 v[24:27], v[186:189], v[218:221], v[24:27]
	v_mfma_f32_16x16x32_bf16 v[20:23], v[194:197], v[218:221], v[20:23]
	v_mfma_f32_16x16x32_bf16 v[8:11], v[186:189], v[226:229], v[8:11]
	v_mfma_f32_16x16x32_bf16 v[4:7], v[194:197], v[226:229], v[4:7]
	s_setprio 0
	s_barrier
; #define PG8_STAGE(bufoff, gbase, voff) do { _Pragma("unroll") for (int _i = 0; _i < 2; ++_i) \
;         __builtin_amdgcn_global_load_lds((const unsigned*)((const char*)(gbase) + (voff)[_i]), (PG8_LAS unsigned*)(lds + (bufoff) + ldsw + _i * 8192), 16, 0, 0); } while (0)
; #define PG8_LDA(dst, b, h) do { _Pragma("unroll") for (int m = 0; m < 4; ++m) _Pragma("unroll") for (int k = 0; k < 2; ++k) dst[m][k] = *(const PG8_LAS bf16x8*)(lds + PG8_SA(b, h) + aoff + m * 2048 + k * 1024); } while (0)
; #define PG8_LDB(dst, b, h) do { _Pragma("unroll") for (int n = 0; n < 2; ++n) _Pragma("unroll") for (int k = 0; k < 2; ++k) dst[n][k] = *(const PG8_LAS bf16x8*)(lds + PG8_SB(b, h) + boff + n * 2048 + k * 1024); } while (0)
; #define PG8_MMA(ai, bj, At, Bt) do { __builtin_amdgcn_s_setprio(1); _Pragma("unroll") for (int m = 0; m < 4; ++m) _Pragma("unroll") for (int n = 0; n < 2; ++n) _Pragma("unroll") for (int k = 0; k < 2; ++k) \
;         acc[ai][bj][m][n] = __builtin_amdgcn_mfma_f32_16x16x32_bf16(Bt[n][k], At[m][k], acc[ai][bj][m][n], 0, 0, 0); __builtin_amdgcn_s_setprio(0); } while (0)
; #define PG8_WAIT_V(n) asm volatile("s_waitcnt vmcnt(" #n ")" ::: "memory")
; #define PG8_WAIT_L(n) asm volatile("s_waitcnt lgkmcnt(" #n ")" ::: "memory")
; #define PG8_BAR __builtin_amdgcn_s_barrier()
; #define PG8_SCHED __builtin_amdgcn_sched_barrier(0)
; template <class Epi, class Sched, bool ALIGN_EPI = false, bool SP2 = false>
; __device__ __forceinline__ void gemm_phase(PG8_LAS unsigned char* lds, const Gemm g, const Sched& S, const Epi& E, const int tid) {
;     ...
;             PG8_LDB(B0, 1, 0); PG8_LDB(B1, 1, 1); PG8_SCHED; PG8_LDA(At, 1, 0); PG8_STAGE(PG8_SA(0, 1), a2 + hstep, voffA);
;             PG8_WAIT_V(8); PG8_WAIT_L(0); PG8_BAR; PG8_MMA(0, 0, At, B0); PG8_MMA(0, 1, At, B1); PG8_BAR; PG8_SCHED;
;             PG8_LDA(At, 1, 1); PG8_STAGE(PG8_SB(1, 0), b3, voffB); PG8_STAGE(PG8_SB(1, 1), b3 + hstep, voffB); PG8_STAGE(PG8_SA(1, 0), a3, voffA);
;             PG8_WAIT_V(8); PG8_WAIT_L(0); PG8_BAR; PG8_MMA(1, 0, At, B0); PG8_MMA(1, 1, At, B1); PG8_BAR; PG8_SCHED;
	s_add_i32 s42, 0, 0x18000
	v_add_u32_e32 v138, s42, v161
	s_add_i32 s43, 0, 0x1c000
	ds_read_b128 v[140:143], v138
	ds_read_b128 v[144:147], v138 offset:1024
	ds_read_b128 v[166:169], v138 offset:2048
	ds_read_b128 v[170:173], v138 offset:3072
	v_add_u32_e32 v138, s43, v161
	ds_read_b128 v[174:177], v138
	ds_read_b128 v[186:189], v138 offset:1024
	ds_read_b128 v[190:193], v138 offset:2048
	ds_read_b128 v[194:197], v138 offset:3072
	s_add_u32 s28, s28, 0x80000
	s_addc_u32 s29, s29, 0
	s_mov_b32 m0, s44
	s_nop 0
	ds_read_b128 v[198:201], v165 offset:32768
	ds_read_b128 v[202:205], v165 offset:33792
	ds_read_b128 v[206:209], v165 offset:34816
	ds_read_b128 v[210:213], v165 offset:35840
	ds_read_b128 v[214:217], v165 offset:36864
	ds_read_b128 v[218:221], v165 offset:37888
	ds_read_b128 v[222:225], v165 offset:38912
	ds_read_b128 v[226:229], v165 offset:39936
	global_load_lds_dwordx4 v150, s[28:29]
	s_nop 0
	s_mov_b32 m0, s48
	s_nop 0
	global_load_lds_dwordx4 v148, s[28:29]
	s_waitcnt vmcnt(8)
	s_waitcnt lgkmcnt(0)
	s_setprio 1
	s_barrier
	v_mfma_f32_16x16x32_bf16 v[134:137], v[140:143], v[198:201], v[134:137]
	v_mfma_f32_16x16x32_bf16 v[124:127], v[166:169], v[198:201], v[124:127]
	v_mfma_f32_16x16x32_bf16 v[112:115], v[140:143], v[206:209], v[112:115]
	v_mfma_f32_16x16x32_bf16 v[108:111], v[166:169], v[206:209], v[108:111]
	v_mfma_f32_16x16x32_bf16 v[96:99], v[140:143], v[214:217], v[96:99]
	v_mfma_f32_16x16x32_bf16 v[92:95], v[166:169], v[214:217], v[92:95]
	v_mfma_f32_16x16x32_bf16 v[80:83], v[140:143], v[222:225], v[80:83]
	v_mfma_f32_16x16x32_bf16 v[76:79], v[166:169], v[222:225], v[76:79]
	v_mfma_f32_16x16x32_bf16 v[136:139], v[144:147], v[202:205], v[134:137]
	v_mfma_f32_16x16x32_bf16 v[124:127], v[170:173], v[202:205], v[124:127]
	v_mfma_f32_16x16x32_bf16 v[112:115], v[144:147], v[210:213], v[112:115]
	v_mfma_f32_16x16x32_bf16 v[108:111], v[170:173], v[210:213], v[108:111]
	v_mfma_f32_16x16x32_bf16 v[96:99], v[144:147], v[218:221], v[96:99]
	v_mfma_f32_16x16x32_bf16 v[92:95], v[170:173], v[218:221], v[92:95]
	v_mfma_f32_16x16x32_bf16 v[80:83], v[144:147], v[226:229], v[80:83]
	v_mfma_f32_16x16x32_bf16 v[76:79], v[170:173], v[226:229], v[76:79]
	s_setprio 0
	s_setprio 1
	v_mfma_f32_16x16x32_bf16 v[120:123], v[174:177], v[198:201], v[120:123]
	v_mfma_f32_16x16x32_bf16 v[116:119], v[190:193], v[198:201], v[116:119]
	v_mfma_f32_16x16x32_bf16 v[104:107], v[174:177], v[206:209], v[104:107]
	v_mfma_f32_16x16x32_bf16 v[100:103], v[190:193], v[206:209], v[100:103]
	v_mfma_f32_16x16x32_bf16 v[88:91], v[174:177], v[214:217], v[88:91]
	v_mfma_f32_16x16x32_bf16 v[84:87], v[190:193], v[214:217], v[84:87]
	v_mfma_f32_16x16x32_bf16 v[72:75], v[174:177], v[222:225], v[72:75]
	v_mfma_f32_16x16x32_bf16 v[68:71], v[190:193], v[222:225], v[68:71]
	v_mfma_f32_16x16x32_bf16 v[120:123], v[186:189], v[202:205], v[120:123]
	v_mfma_f32_16x16x32_bf16 v[116:119], v[194:197], v[202:205], v[116:119]
	v_mfma_f32_16x16x32_bf16 v[104:107], v[186:189], v[210:213], v[104:107]
	v_mfma_f32_16x16x32_bf16 v[100:103], v[194:197], v[210:213], v[100:103]
	v_mfma_f32_16x16x32_bf16 v[88:91], v[186:189], v[218:221], v[88:91]
	v_mfma_f32_16x16x32_bf16 v[84:87], v[194:197], v[218:221], v[84:87]
	v_mfma_f32_16x16x32_bf16 v[72:75], v[186:189], v[226:229], v[72:75]
	v_mfma_f32_16x16x32_bf16 v[68:71], v[194:197], v[226:229], v[68:71]
	s_setprio 0
	s_barrier
	s_add_i32 s28, s42, s31
	v_lshl_add_u64 v[134:135], v[178:179], 0, s[46:47]
	s_mov_b32 m0, s28
	ds_read_b128 v[198:201], v165 offset:49152
	ds_read_b128 v[202:205], v165 offset:50176
	ds_read_b128 v[206:209], v165 offset:51200
	ds_read_b128 v[210:213], v165 offset:52224
	ds_read_b128 v[214:217], v165 offset:53248
	ds_read_b128 v[218:221], v165 offset:54272
	ds_read_b128 v[222:225], v165 offset:55296
	ds_read_b128 v[226:229], v165 offset:56320
	global_load_lds_dwordx4 v[134:135], off
	s_add_i32 m0, s28, 0x2000
	s_add_u32 s26, s26, 0x80080
	v_lshl_add_u64 v[134:135], v[180:181], 0, s[46:47]
	s_addc_u32 s27, s27, 0
	s_add_i32 s28, s43, s31
	global_load_lds_dwordx4 v[134:135], off
	s_nop 0
	s_mov_b32 m0, s28
	s_nop 0
	global_load_lds_dwordx4 v2, s[26:27]
	v_lshl_add_u64 v[134:135], s[26:27], 0, v[0:1]
	s_add_i32 m0, s28, 0x2000
	s_nop 0
	global_load_lds_dwordx4 v[134:135], off
	v_lshl_add_u64 v[134:135], v[182:183], 0, s[46:47]
	s_mov_b32 m0, s52
	s_nop 0
	global_load_lds_dwordx4 v[134:135], off
	v_lshl_add_u64 v[134:135], v[230:231], 0, s[46:47]
	s_mov_b32 m0, s53
	s_nop 0
	global_load_lds_dwordx4 v[134:135], off
	s_waitcnt vmcnt(8)
	s_waitcnt lgkmcnt(0)
	s_setprio 1
	s_barrier
	v_mfma_f32_16x16x32_bf16 v[64:67], v[140:143], v[198:201], v[64:67]
	v_mfma_f32_16x16x32_bf16 v[60:63], v[166:169], v[198:201], v[60:63]
	v_mfma_f32_16x16x32_bf16 v[48:51], v[140:143], v[206:209], v[48:51]
	v_mfma_f32_16x16x32_bf16 v[44:47], v[166:169], v[206:209], v[44:47]
	v_mfma_f32_16x16x32_bf16 v[32:35], v[140:143], v[214:217], v[32:35]
	v_mfma_f32_16x16x32_bf16 v[28:31], v[166:169], v[214:217], v[28:31]
	v_mfma_f32_16x16x32_bf16 v[16:19], v[140:143], v[222:225], v[16:19]
	v_mfma_f32_16x16x32_bf16 v[12:15], v[166:169], v[222:225], v[12:15]
	v_mfma_f32_16x16x32_bf16 v[64:67], v[144:147], v[202:205], v[64:67]
	v_mfma_f32_16x16x32_bf16 v[60:63], v[170:173], v[202:205], v[60:63]
	v_mfma_f32_16x16x32_bf16 v[48:51], v[144:147], v[210:213], v[48:51]
	v_mfma_f32_16x16x32_bf16 v[44:47], v[170:173], v[210:213], v[44:47]
	v_mfma_f32_16x16x32_bf16 v[32:35], v[144:147], v[218:221], v[32:35]
	v_mfma_f32_16x16x32_bf16 v[28:31], v[170:173], v[218:221], v[28:31]
	v_mfma_f32_16x16x32_bf16 v[16:19], v[144:147], v[226:229], v[16:19]
	v_mfma_f32_16x16x32_bf16 v[12:15], v[170:173], v[226:229], v[12:15]
	s_setprio 0
	s_setprio 1
	v_mfma_f32_16x16x32_bf16 v[56:59], v[174:177], v[198:201], v[56:59]
	v_mfma_f32_16x16x32_bf16 v[52:55], v[190:193], v[198:201], v[52:55]
	v_mfma_f32_16x16x32_bf16 v[40:43], v[174:177], v[206:209], v[40:43]
	v_mfma_f32_16x16x32_bf16 v[36:39], v[190:193], v[206:209], v[36:39]
	v_mfma_f32_16x16x32_bf16 v[24:27], v[174:177], v[214:217], v[24:27]
	v_mfma_f32_16x16x32_bf16 v[20:23], v[190:193], v[214:217], v[20:23]
	v_mfma_f32_16x16x32_bf16 v[8:11], v[174:177], v[222:225], v[8:11]
	v_mfma_f32_16x16x32_bf16 v[4:7], v[190:193], v[222:225], v[4:7]
	v_mfma_f32_16x16x32_bf16 v[56:59], v[186:189], v[202:205], v[56:59]
	v_mfma_f32_16x16x32_bf16 v[52:55], v[194:197], v[202:205], v[52:55]
	v_mfma_f32_16x16x32_bf16 v[40:43], v[186:189], v[210:213], v[40:43]
	v_mfma_f32_16x16x32_bf16 v[36:39], v[194:197], v[210:213], v[36:39]
	v_mfma_f32_16x16x32_bf16 v[24:27], v[186:189], v[218:221], v[24:27]
	v_mfma_f32_16x16x32_bf16 v[20:23], v[194:197], v[218:221], v[20:23]
	v_mfma_f32_16x16x32_bf16 v[8:11], v[186:189], v[226:229], v[8:11]
	v_mfma_f32_16x16x32_bf16 v[4:7], v[194:197], v[226:229], v[4:7]
	s_setprio 0
	s_barrier
	s_add_i32 s51, s51, 2
	s_add_u32 s24, s24, 0x100
	s_addc_u32 s25, s25, 0
	s_add_u32 s23, s23, 0x100
	s_addc_u32 s50, s50, 0
	s_cmp_gt_u32 s51, 29
	s_cbranch_scc1 .LBB0_269
